# P7 item 1: the 15 serialized LDS read -> MFMA round trips batched five at a time into dead registers with counted waits (on top of the prefetch drain removal)
# speedup vs baseline: 1.0043x; 1.0043x over previous
.LBB0_1471:
	s_movk_i32 s56, 0x110
	v_mad_u64_u32 v[230:231], s[50:51], v183, s56, v[178:179]
	v_mad_u64_u32 v[232:233], s[50:51], v229, s56, v[178:179]
	v_mad_u64_u32 v[228:229], s[50:51], v228, s56, v[178:179]
	ds_read_b128 v[146:149], v211 offset:54272
	ds_read_b128 v[162:165], v215
	ds_read_b128 v[150:153], v230 offset:54272
	ds_read_b128 v[158:161], v228 offset:54272
	ds_read_b128 v[154:157], v232 offset:54272
	ds_read_b128 v[2:5], v211 offset:54336
	ds_read_b128 v[6:9], v230 offset:54336
	ds_read_b128 v[10:13], v232 offset:54336
	ds_read_b128 v[14:17], v228 offset:54336
	ds_read_b128 v[18:21], v215 offset:64
	s_waitcnt lgkmcnt(9)
	v_mfma_f32_16x16x32_bf16 v[146:149], v[146:149], v[126:129], 0
	s_mov_b32 s37, 0
	s_waitcnt lgkmcnt(7)
	v_mfma_f32_16x16x32_bf16 v[150:153], v[150:153], v[126:129], 0
	s_waitcnt lgkmcnt(5)
	v_mfma_f32_16x16x32_bf16 v[154:157], v[154:157], v[126:129], 0
	v_mfma_f32_16x16x32_bf16 v[158:161], v[158:161], v[126:129], 0
	v_mfma_f32_16x16x32_bf16 v[126:129], v[162:165], v[126:129], 0
	ds_read_b128 v[22:25], v211 offset:54400
	ds_read_b128 v[26:29], v230 offset:54400
	ds_read_b128 v[30:33], v232 offset:54400
	ds_read_b128 v[34:37], v228 offset:54400
	ds_read_b128 v[38:41], v215 offset:128
	s_waitcnt lgkmcnt(9)
	v_mfma_f32_16x16x32_bf16 v[146:149], v[2:5], v[122:125], v[146:149]
	s_waitcnt lgkmcnt(8)
	v_mfma_f32_16x16x32_bf16 v[150:153], v[6:9], v[122:125], v[150:153]
	s_waitcnt lgkmcnt(7)
	v_mfma_f32_16x16x32_bf16 v[154:157], v[10:13], v[122:125], v[154:157]
	s_waitcnt lgkmcnt(6)
	v_mfma_f32_16x16x32_bf16 v[158:161], v[14:17], v[122:125], v[158:161]
	s_waitcnt lgkmcnt(5)
	v_mfma_f32_16x16x32_bf16 v[122:125], v[18:21], v[122:125], v[126:129]
	ds_read_b128 v[42:45], v211 offset:54464
	ds_read_b128 v[238:241], v230 offset:54464
	ds_read_b128 v[242:245], v232 offset:54464
	ds_read_b128 v[246:249], v228 offset:54464
	ds_read_b128 v[2:5], v215 offset:192
	s_waitcnt lgkmcnt(9)
	v_mfma_f32_16x16x32_bf16 v[126:129], v[22:25], v[118:121], v[146:149]
	s_waitcnt lgkmcnt(8)
	v_mfma_f32_16x16x32_bf16 v[146:149], v[26:29], v[118:121], v[150:153]
	s_waitcnt lgkmcnt(7)
	v_mfma_f32_16x16x32_bf16 v[150:153], v[30:33], v[118:121], v[154:157]
	s_waitcnt lgkmcnt(6)
	v_mfma_f32_16x16x32_bf16 v[154:157], v[34:37], v[118:121], v[158:161]
	s_waitcnt lgkmcnt(5)
	v_mfma_f32_16x16x32_bf16 v[118:121], v[38:41], v[118:121], v[122:125]
	s_waitcnt lgkmcnt(4)
	v_mfma_f32_16x16x32_bf16 v[122:125], v[42:45], v[114:117], v[126:129]
	s_waitcnt lgkmcnt(3)
	v_mfma_f32_16x16x32_bf16 v[146:149], v[238:241], v[114:117], v[146:149]
	s_waitcnt lgkmcnt(2)
	v_mfma_f32_16x16x32_bf16 v[150:153], v[242:245], v[114:117], v[150:153]
	s_waitcnt lgkmcnt(1)
	v_mfma_f32_16x16x32_bf16 v[154:157], v[246:249], v[114:117], v[154:157]
	s_waitcnt lgkmcnt(0)
	v_mfma_f32_16x16x32_bf16 v[114:117], v[2:5], v[114:117], v[118:121]
	s_nop 7
	ds_bpermute_b32 v115, v207, v181
	ds_bpermute_b32 v114, v217, v114
	s_waitcnt lgkmcnt(1)
	v_add_f32_e32 v115, v181, v115
	ds_bpermute_b32 v116, v208, v115
	s_waitcnt lgkmcnt(1)
	v_mul_f32_e32 v114, v194, v114
	s_waitcnt lgkmcnt(0)
	v_add_f32_e32 v115, v115, v116
	v_fmac_f32_e32 v114, v173, v115
	v_max_f32_e32 v115, v195, v195
	v_max_f32_e64 v114, |v114|, v115
	v_rcp_f32_e32 v115, v114
	v_mul_f32_e32 v114, v194, v122
	v_fmac_f32_e32 v114, v173, v142
	v_mul_f32_e32 v128, v114, v115
	v_mul_f32_e32 v114, v194, v123
	v_fmac_f32_e32 v114, v173, v143
	v_mul_f32_e32 v129, v114, v115
	v_mul_f32_e32 v114, v194, v124
	v_fmac_f32_e32 v114, v173, v144
	v_mul_f32_e32 v126, v114, v115
	v_mul_f32_e32 v114, v194, v125
	v_fmac_f32_e32 v114, v173, v145
	v_mul_f32_e32 v127, v114, v115
	v_mul_f32_e32 v114, v194, v146
	v_fmac_f32_e32 v114, v173, v138
	v_mul_f32_e32 v124, v114, v115
	v_mul_f32_e32 v114, v194, v147
	v_fmac_f32_e32 v114, v173, v139
	v_mul_f32_e32 v125, v114, v115
	v_mul_f32_e32 v114, v194, v148
	v_fmac_f32_e32 v114, v173, v140
	v_mul_f32_e32 v122, v114, v115
	v_mul_f32_e32 v114, v194, v149
	v_fmac_f32_e32 v114, v173, v141
	v_mul_f32_e32 v123, v114, v115
	v_mul_f32_e32 v114, v194, v150
	v_mul_f32_e32 v142, v129, v129
	v_fmac_f32_e32 v114, v173, v134
	v_fmac_f32_e32 v142, v128, v128
	v_mul_f32_e32 v120, v114, v115
	v_mul_f32_e32 v114, v194, v151
	v_fmac_f32_e32 v142, v126, v126
	v_fmac_f32_e32 v114, v173, v135
	v_fmac_f32_e32 v142, v127, v127
	v_mul_f32_e32 v121, v114, v115
	v_mul_f32_e32 v114, v194, v152
	v_fmac_f32_e32 v142, v124, v124
	v_fmac_f32_e32 v114, v173, v136
	v_fmac_f32_e32 v142, v125, v125
	v_mul_f32_e32 v118, v114, v115
	v_mul_f32_e32 v114, v194, v153
	v_fmac_f32_e32 v142, v122, v122
	v_fmac_f32_e32 v114, v173, v137
	v_fmac_f32_e32 v142, v123, v123
	v_mul_f32_e32 v119, v114, v115
	v_mul_f32_e32 v114, v194, v154
	v_fmac_f32_e32 v142, v120, v120
	v_fmac_f32_e32 v114, v173, v130
	v_fmac_f32_e32 v142, v121, v121
	v_mul_f32_e32 v116, v114, v115
	v_mul_f32_e32 v114, v194, v155
	v_fmac_f32_e32 v142, v118, v118
	v_fmac_f32_e32 v114, v173, v131
	v_fmac_f32_e32 v142, v119, v119
	v_mul_f32_e32 v117, v114, v115
	v_mul_f32_e32 v114, v194, v156
	v_fmac_f32_e32 v142, v116, v116
	v_fmac_f32_e32 v114, v173, v132
	v_mul_f32_e32 v130, v194, v157
	v_fmac_f32_e32 v142, v117, v117
	v_mul_f32_e32 v114, v114, v115
	v_fmac_f32_e32 v130, v173, v133
	v_fmac_f32_e32 v142, v114, v114
	v_mul_f32_e32 v115, v130, v115
	v_fmac_f32_e32 v142, v115, v115
	ds_bpermute_b32 v130, v207, v142
	s_waitcnt lgkmcnt(0)
	v_add_f32_e32 v130, v142, v130
	ds_bpermute_b32 v131, v208, v130
	s_and_saveexec_b64 s[66:67], s[22:23]
	s_cbranch_execz .LBB0_1473
	s_lshl_b32 s50, s55, 2
	s_add_i32 s50, s50, 0
	s_add_i32 s50, s50, s73
	s_waitcnt lgkmcnt(0)
	v_add_f32_e32 v130, v130, v131
	v_lshl_add_u32 v131, v171, 2, s50
	v_add_u32_e32 v131, 0x17100, v131
	ds_write_b32 v131, v130
